# attention V-tile LDS swizzle only (on top of v35)
# speedup vs baseline: 1.0422x; 1.0007x over previous
.LBB0_853:
	s_andn2_saveexec_b64 s[52:53], s[42:43]
	s_cbranch_execz .LBB0_871
	v_subrev_u32_e32 v0, 32, v104
	v_lshrrev_b32_e32 v0, 5, v0
	v_sub_u32_e32 v78, 31, v0
	v_mov_b32_e32 v0, v178
	v_readfirstlane_b32 s100, v178
	s_lshr_b32 s100, s100, 6
	s_mov_b32 s12, 0x2aaaaaab
	v_and_b32_e32 v181, 7, v104
	v_mul_u32_u24_e32 v2, 0x60, v181
	v_mul_hi_i32 v4, v0, s12
	v_readlane_b32 s0, v236, 58
	v_lshrrev_b32_e32 v6, 31, v4
	v_ashrrev_i32_e32 v4, 1, v4
	v_bfe_u32 v1, v104, 3, 2
	v_lshlrev_b32_e32 v2, 1, v2
	v_readlane_b32 s1, v236, 59
	v_add_u32_e32 v80, v4, v6
	v_mul_lo_u32 v4, v80, s75
	v_lshl_add_u64 v[24:25], s[0:1], 0, v[2:3]
	v_mad_u64_u32 v[26:27], s[0:1], v80, -12, v[0:1]
	v_lshl_add_u32 v168, v26, 3, v4
	v_add_u32_e32 v4, 0x100, v0
	v_mul_hi_i32 v6, v4, s12
	v_lshrrev_b32_e32 v7, 31, v6
	v_ashrrev_i32_e32 v6, 1, v6
	v_mul_u32_u24_e32 v5, 0x300000, v1
	v_add_u32_e32 v27, v6, v7
	v_mad_u64_u32 v[28:29], s[0:1], v27, -12, v[4:5]
	v_mul_lo_u32 v6, v27, s75
	v_lshl_add_u32 v170, v28, 3, v6
	v_add_u32_e32 v6, 0x200, v0
	v_mul_hi_i32 v7, v6, s12
	v_lshrrev_b32_e32 v8, 31, v7
	v_ashrrev_i32_e32 v7, 1, v7
	v_add_u32_e32 v29, v7, v8
	v_mad_u64_u32 v[30:31], s[0:1], v29, -12, v[6:7]
	v_and_b32_e32 v79, 15, v0
	v_mul_lo_u32 v6, v29, s75
	v_readlane_b32 s0, v236, 60
	v_and_b32_e32 v31, 7, v0
	v_ashrrev_i32_e32 v81, 3, v0
	v_bfe_u32 v83, v0, 4, 2
	v_ashrrev_i32_e32 v0, 1, v0
	v_lshl_add_u32 v172, v30, 3, v6
	v_lshlrev_b32_e32 v6, 1, v5
	v_mov_b32_e32 v7, v3
	v_readlane_b32 s1, v236, 61
	v_and_b32_e32 v0, 0xffffffe0, v0
	v_lshl_add_u32 v204, v78, 7, v0
	v_lshl_add_u64 v[6:7], s[0:1], 0, v[6:7]
	v_lshl_add_u64 v[174:175], v[6:7], 0, v[2:3]
	v_lshlrev_b32_e32 v2, 3, v31
	v_ashrrev_i32_e32 v82, 3, v4
	v_lshl_add_u32 v0, v1, 12, v204
	v_lshl_or_b32 v176, v81, 12, v2
	v_lshl_or_b32 v182, v82, 12, v2
	v_lshlrev_b32_e32 v2, 19, v181
	v_readlane_b32 s0, v236, 62
	v_or_b32_e32 v166, v0, v79
	v_lshlrev_b32_e32 v76, 4, v83
	v_mov_b32_e32 v77, v3
	v_ashrrev_i32_e32 v169, 31, v168
	v_ashrrev_i32_e32 v171, 31, v170
	v_ashrrev_i32_e32 v173, 31, v172
	v_lshl_or_b32 v2, v1, 22, v2
	v_readlane_b32 s1, v236, 63
	v_lshl_add_u64 v[24:25], v[24:25], 0, v[76:77]
	v_or_b32_e32 v0, 16, v166
	v_lshlrev_b64 v[56:57], 1, v[168:169]
	v_lshlrev_b64 v[58:59], 1, v[170:171]
	v_lshlrev_b64 v[60:61], 1, v[172:173]
	v_lshl_add_u64 v[184:185], s[0:1], 0, v[2:3]
	v_ashrrev_i32_e32 v177, 31, v176
	v_ashrrev_i32_e32 v183, 31, v182
	v_mad_i64_i32 v[40:41], s[0:1], v166, s79, v[24:25]
	v_mad_i64_i32 v[24:25], s[0:1], v0, s79, v[24:25]
	v_lshl_add_u64 v[4:5], v[174:175], 0, v[56:57]
	v_lshl_add_u64 v[8:9], v[174:175], 0, v[58:59]
	v_lshl_add_u64 v[12:13], v[174:175], 0, v[60:61]
	v_lshl_add_u64 v[62:63], v[176:177], 1, v[184:185]
	v_lshl_add_u64 v[72:73], v[182:183], 1, v[184:185]
	s_mov_b64 s[0:1], 0x18000
	global_load_dwordx4 v[4:7], v[4:5], off
	s_nop 0
	global_load_dwordx4 v[8:11], v[8:9], off
	s_movk_i32 s12, 0x90
	global_load_dwordx4 v[12:15], v[12:13], off
	v_lshlrev_b32_e32 v205, 1, v78
	global_load_dwordx4 v[16:19], v[62:63], off
	global_load_dwordx4 v[20:23], v[72:73], off
	global_load_dwordx4 v[32:35], v[40:41], off
	global_load_dwordx4 v[36:39], v[40:41], off offset:64
	s_nop 0
	global_load_dwordx4 v[40:43], v[40:41], off offset:128
	s_nop 0
	global_load_dwordx4 v[44:47], v[24:25], off
	global_load_dwordx4 v[48:51], v[24:25], off offset:64
	global_load_dwordx4 v[52:55], v[24:25], off offset:128
	v_lshl_add_u64 v[24:25], v[174:175], 0, s[0:1]
	v_lshl_add_u64 v[74:75], v[24:25], 0, v[56:57]
	v_lshl_add_u64 v[56:57], v[24:25], 0, v[58:59]
	v_lshl_add_u64 v[24:25], v[24:25], 0, v[60:61]
	global_load_dwordx4 v[56:59], v[56:57], off
	s_nop 0
	global_load_dwordx4 v[64:67], v[24:25], off
	global_load_dwordx4 v[68:71], v[62:63], off offset:128
	s_nop 0
	global_load_dwordx4 v[60:63], v[74:75], off
	s_nop 0
	global_load_dwordx4 v[72:75], v[72:73], off offset:128
	s_movk_i32 s0, 0xe0
	v_mul_lo_u32 v2, v80, s0
	v_lshl_add_u32 v206, v26, 4, v2
	v_mul_lo_u32 v2, v27, s0
	v_lshl_add_u32 v207, v28, 4, v2
	v_mul_lo_u32 v2, v29, s0
	v_lshl_add_u32 v208, v30, 4, v2
	v_lshlrev_b32_e32 v2, 4, v31
	v_bfe_u32 v24, v79, 3, 1
	v_xor_b32_e32 v24, v24, v83
	v_lshlrev_b32_e32 v24, 3, v24
	s_waitcnt vmcnt(15)
	ds_write_b128 v206, v[4:7]
	s_waitcnt vmcnt(14)
	ds_write_b128 v207, v[8:11]
	s_waitcnt vmcnt(13)
	ds_write_b128 v208, v[12:15]
	v_mad_u64_u32 v[186:187], s[0:1], v81, s12, v[2:3]
	v_mad_u64_u32 v[188:189], s[0:1], v82, s12, v[2:3]
	v_mul_u32_u24_e32 v8, 0xe0, v79
	v_mul_u32_u24_e32 v9, 0x90, v79
	v_mov_b32_e32 v6, v3
	v_mov_b32_e32 v7, v3
	s_waitcnt vmcnt(12)
	s_bitcmp1_b32 s100, 0
	s_cbranch_scc0 .Lattn_nosw_1
	v_swap_b32 v16, v18
	v_swap_b32 v17, v19
.Lattn_nosw_1:
	ds_write_b128 v186, v[16:19] offset:14336
	s_waitcnt vmcnt(11)
	s_bitcmp1_b32 s100, 0
	s_cbranch_scc0 .Lattn_nosw_2
	v_swap_b32 v20, v22
	v_swap_b32 v21, v23
.Lattn_nosw_2:
	ds_write_b128 v188, v[20:23] offset:14336
	v_or_b32_e32 v210, v204, v79
	v_mov_b32_e32 v2, v3
	v_mov_b32_e32 v4, v3
	v_mov_b32_e32 v5, v3
	v_add_u32_e32 v212, v8, v76
	v_add_u32_e32 v213, v24, v9
	v_mov_b64_e32 v[22:23], v[6:7]
	v_mov_b64_e32 v[10:11], v[6:7]
	v_mov_b64_e32 v[26:27], v[6:7]
	v_mov_b64_e32 v[14:15], v[6:7]
	v_mov_b64_e32 v[30:31], v[6:7]
	v_mov_b64_e32 v[18:19], v[6:7]
	v_mov_b64_e32 v[98:99], v[6:7]
	s_mov_b32 s61, 3
	v_ashrrev_i32_e32 v167, 31, v166
	v_ashrrev_i32_e32 v1, 31, v0
	v_add_u32_e32 v209, 2, v205
	v_or_b32_e32 v189, 31, v204
	v_lshlrev_b32_e32 v187, 2, v83
	v_or_b32_e32 v211, 16, v210
	v_mov_b32_e32 v215, 0xf149f2ca
	s_movk_i32 s56, 0xc0
	s_mov_b64 s[54:55], 0
	v_mov_b64_e32 v[20:21], v[4:5]
	v_mov_b64_e32 v[8:9], v[4:5]
	v_mov_b64_e32 v[24:25], v[4:5]
	v_mov_b64_e32 v[12:13], v[4:5]
	v_mov_b64_e32 v[28:29], v[4:5]
	v_mov_b64_e32 v[16:17], v[4:5]
	v_mov_b64_e32 v[96:97], v[4:5]
	v_mov_b32_e32 v214, 0xf149f2ca
	v_mov_b64_e32 v[164:165], v[2:3]
	s_waitcnt lgkmcnt(0)
	s_barrier
	s_branch .LBB0_856

.LBB0_862:
	s_or_b64 exec, exec, s[40:41]
	v_cmp_lt_u32_e64 s[0:1], s61, v209
	s_waitcnt vmcnt(1)
	ds_write_b128 v206, v[60:63] offset:23552
	ds_write_b128 v207, v[56:59] offset:23552
	ds_write_b128 v208, v[64:67] offset:23552
	s_bitcmp1_b32 s100, 0
	s_cbranch_scc0 .Lattn_nosw_3
	v_swap_b32 v68, v70
	v_swap_b32 v69, v71
.Lattn_nosw_3:
	ds_write_b128 v186, v[68:71] offset:37888
	s_waitcnt vmcnt(0)
	s_bitcmp1_b32 s100, 0
	s_cbranch_scc0 .Lattn_nosw_4
	v_swap_b32 v72, v74
	v_swap_b32 v73, v75
.Lattn_nosw_4:
	ds_write_b128 v188, v[72:75] offset:37888
	s_waitcnt lgkmcnt(0)
	s_barrier
	s_and_saveexec_b64 s[12:13], s[0:1]
	s_cbranch_execz .LBB0_864
	s_mov_b32 s57, s35
	v_mad_u64_u32 v[64:65], s[0:1], s56, v202, v[174:175]
	v_lshl_add_u64 v[72:73], s[56:57], 1, v[184:185]
	v_lshl_add_u64 v[56:57], v[168:169], 1, v[64:65]
	v_lshl_add_u64 v[58:59], v[170:171], 1, v[64:65]
	v_lshl_add_u64 v[64:65], v[172:173], 1, v[64:65]
	v_lshl_add_u64 v[68:69], v[176:177], 1, v[72:73]
	v_lshl_add_u64 v[72:73], v[182:183], 1, v[72:73]
	global_load_dwordx4 v[60:63], v[56:57], off
	s_nop 0
	global_load_dwordx4 v[56:59], v[58:59], off
	s_nop 0
	global_load_dwordx4 v[64:67], v[64:65], off
	s_nop 0
	global_load_dwordx4 v[68:71], v[68:69], off
	s_nop 0
	global_load_dwordx4 v[72:75], v[72:73], off

.LBB0_868:
	s_or_b64 exec, exec, s[40:41]
	s_and_saveexec_b64 s[0:1], vcc
	s_cbranch_execz .LBB0_855
	ds_write_b128 v206, v[80:83]
	ds_write_b128 v207, v[76:79]
	ds_write_b128 v208, v[84:87]
	s_bitcmp1_b32 s100, 0
	s_cbranch_scc0 .Lattn_nosw_5
	v_swap_b32 v88, v90
	v_swap_b32 v89, v91
.Lattn_nosw_5:
	ds_write_b128 v186, v[88:91] offset:14336
	s_bitcmp1_b32 s100, 0
	s_cbranch_scc0 .Lattn_nosw_6
	v_swap_b32 v92, v94
	v_swap_b32 v93, v95
.Lattn_nosw_6:
	ds_write_b128 v188, v[92:95] offset:14336
	s_branch .LBB0_855
